# grid sync: first workgroup of each XCD to arrive starts an early L2 write-back
# baseline (speedup 1.0000x reference)
; __device__ __forceinline__ int fresh_lane() { int l; asm volatile("v_mbcnt_lo_u32_b32 %0, -1, 0\n\tv_mbcnt_hi_u32_b32 %0, -1, %0" : "=v"(l)); return l; }
; __device__ __forceinline__ unsigned bar_ld(unsigned* p) { return __hip_atomic_load(p, __ATOMIC_RELAXED, __HIP_MEMORY_SCOPE_AGENT); }
; __device__ __forceinline__ unsigned bar_add(unsigned* p) { return __hip_atomic_fetch_add(p, 1u, __ATOMIC_RELAXED, __HIP_MEMORY_SCOPE_AGENT); }
; __device__ __forceinline__ void grid_bar(unsigned* bar, unsigned k, unsigned x, unsigned nloc, unsigned nx, int wave0) {
;     ...
;     if (wave0 == 0) {
;         const int ln = fresh_lane();
;         if (ln == 0) {
;             const unsigned old = bar_add(&bar[1024 + 64 * x]);
;             if (old + 1u == k * nloc) {
;                 __builtin_amdgcn_fence(__ATOMIC_RELEASE, "agent");
;                 asm volatile("s_waitcnt vmcnt(0)" ::: "memory");
;                 const unsigned og = bar_add(&bar[3072]);
;                 if (og + 1u == k * nx) bar_add(&bar[3136]);
;                 else while (bar_ld(&bar[3136]) < k) __builtin_amdgcn_s_sleep(1);
;                 __builtin_amdgcn_fence(__ATOMIC_ACQUIRE, "agent");
;                 bar_add(&bar[2048 + 64 * x]);
;                 asm volatile("s_waitcnt vmcnt(0)" ::: "memory");
;             } else {
;                 while (bar_ld(&bar[2048 + 64 * x]) < k) __builtin_amdgcn_s_sleep(1);
;                 __builtin_amdgcn_fence(__ATOMIC_ACQUIRE, "agent");
;                 asm volatile("s_waitcnt vmcnt(0)" ::: "memory");
;             }
.LBB0_159:
	s_or_b64 exec, exec, s[2:3]
	s_waitcnt vmcnt(0)
	v_readfirstlane_b32 s2, v2
	s_add_i32 s6, s56, 1
	s_nop 0
	v_add3_u32 v0, s2, v0, 1
	v_readlane_b32 s2, v255, 42
	s_mul_i32 s2, s6, s2
	s_nop 0
	s_mov_b32 s99, s2
	v_cmp_ne_u32_e32 vcc, s2, v0
	s_and_saveexec_b64 s[2:3], vcc
	s_xor_b64 s[2:3], exec, s[2:3]
	s_cbranch_execz .LBB0_163
	v_readlane_b32 s98, v255, 42
	s_sub_i32 s99, s99, s98
	s_add_i32 s99, s99, 1
	v_cmp_eq_u32_e32 vcc, s99, v0
	s_cbranch_vccz .Lgs_np_0
	buffer_wbl2 sc1
.Lgs_np_0:
	global_load_dword v0, v1, s[26:27] sc1
	s_waitcnt vmcnt(0)
	v_cmp_le_u32_e32 vcc, s6, v0
	s_cbranch_vccnz .LBB0_162

; __device__ __forceinline__ int fresh_lane() { int l; asm volatile("v_mbcnt_lo_u32_b32 %0, -1, 0\n\tv_mbcnt_hi_u32_b32 %0, -1, %0" : "=v"(l)); return l; }
; __device__ __forceinline__ unsigned bar_ld(unsigned* p) { return __hip_atomic_load(p, __ATOMIC_RELAXED, __HIP_MEMORY_SCOPE_AGENT); }
; __device__ __forceinline__ unsigned bar_add(unsigned* p) { return __hip_atomic_fetch_add(p, 1u, __ATOMIC_RELAXED, __HIP_MEMORY_SCOPE_AGENT); }
; __device__ __forceinline__ void grid_bar(unsigned* bar, unsigned k, unsigned x, unsigned nloc, unsigned nx, int wave0) {
;     ...
;     if (wave0 == 0) {
;         const int ln = fresh_lane();
;         if (ln == 0) {
;             const unsigned old = bar_add(&bar[1024 + 64 * x]);
;             if (old + 1u == k * nloc) {
;                 __builtin_amdgcn_fence(__ATOMIC_RELEASE, "agent");
;                 asm volatile("s_waitcnt vmcnt(0)" ::: "memory");
;                 const unsigned og = bar_add(&bar[3072]);
;                 if (og + 1u == k * nx) bar_add(&bar[3136]);
;                 else while (bar_ld(&bar[3136]) < k) __builtin_amdgcn_s_sleep(1);
;                 __builtin_amdgcn_fence(__ATOMIC_ACQUIRE, "agent");
;                 bar_add(&bar[2048 + 64 * x]);
;                 asm volatile("s_waitcnt vmcnt(0)" ::: "memory");
;             } else {
;                 while (bar_ld(&bar[2048 + 64 * x]) < k) __builtin_amdgcn_s_sleep(1);
;                 __builtin_amdgcn_fence(__ATOMIC_ACQUIRE, "agent");
;                 asm volatile("s_waitcnt vmcnt(0)" ::: "memory");
;             }
.LBB0_182:
	s_or_b64 exec, exec, s[6:7]
	s_add_i32 s10, s56, 2
	s_waitcnt vmcnt(0)
	v_readfirstlane_b32 s6, v2
	v_readlane_b32 s0, v255, 42
	s_nop 0
	v_add3_u32 v0, s6, v0, 1
	s_mul_i32 s6, s10, s0
	s_mov_b32 s99, s6
	v_cmp_ne_u32_e32 vcc, s6, v0
	s_and_saveexec_b64 s[6:7], vcc
	s_xor_b64 s[6:7], exec, s[6:7]
	s_cbranch_execz .LBB0_186
	v_readlane_b32 s98, v255, 42
	s_sub_i32 s99, s99, s98
	s_add_i32 s99, s99, 1
	v_cmp_eq_u32_e32 vcc, s99, v0
	s_cbranch_vccz .Lgs_np_1
	buffer_wbl2 sc1
.Lgs_np_1:
	global_load_dword v0, v1, s[26:27] sc1
	s_waitcnt vmcnt(0)
	v_cmp_le_u32_e32 vcc, s10, v0
	s_cbranch_vccnz .LBB0_185

; __device__ __forceinline__ int fresh_lane() { int l; asm volatile("v_mbcnt_lo_u32_b32 %0, -1, 0\n\tv_mbcnt_hi_u32_b32 %0, -1, %0" : "=v"(l)); return l; }
; __device__ __forceinline__ unsigned bar_ld(unsigned* p) { return __hip_atomic_load(p, __ATOMIC_RELAXED, __HIP_MEMORY_SCOPE_AGENT); }
; __device__ __forceinline__ unsigned bar_add(unsigned* p) { return __hip_atomic_fetch_add(p, 1u, __ATOMIC_RELAXED, __HIP_MEMORY_SCOPE_AGENT); }
; __device__ __forceinline__ void grid_bar(unsigned* bar, unsigned k, unsigned x, unsigned nloc, unsigned nx, int wave0) {
;     ...
;     if (wave0 == 0) {
;         const int ln = fresh_lane();
;         if (ln == 0) {
;             const unsigned old = bar_add(&bar[1024 + 64 * x]);
;             if (old + 1u == k * nloc) {
;                 __builtin_amdgcn_fence(__ATOMIC_RELEASE, "agent");
;                 asm volatile("s_waitcnt vmcnt(0)" ::: "memory");
;                 const unsigned og = bar_add(&bar[3072]);
;                 if (og + 1u == k * nx) bar_add(&bar[3136]);
;                 else while (bar_ld(&bar[3136]) < k) __builtin_amdgcn_s_sleep(1);
;                 __builtin_amdgcn_fence(__ATOMIC_ACQUIRE, "agent");
;                 bar_add(&bar[2048 + 64 * x]);
;                 asm volatile("s_waitcnt vmcnt(0)" ::: "memory");
;             } else {
;                 while (bar_ld(&bar[2048 + 64 * x]) < k) __builtin_amdgcn_s_sleep(1);
;                 __builtin_amdgcn_fence(__ATOMIC_ACQUIRE, "agent");
;                 asm volatile("s_waitcnt vmcnt(0)" ::: "memory");
;             }
.LBB0_404:
	s_or_b64 exec, exec, s[2:3]
	s_waitcnt vmcnt(0)
	v_readfirstlane_b32 s2, v2
	s_nop 1
	v_add3_u32 v0, s2, v0, 1
	v_readlane_b32 s2, v255, 42
	s_mul_i32 s2, s11, s2
	s_nop 0
	s_mov_b32 s99, s2
	v_cmp_ne_u32_e32 vcc, s2, v0
	s_and_saveexec_b64 s[2:3], vcc
	s_xor_b64 s[2:3], exec, s[2:3]
	s_cbranch_execz .LBB0_408
	v_readlane_b32 s98, v255, 42
	s_sub_i32 s99, s99, s98
	s_add_i32 s99, s99, 1
	v_cmp_eq_u32_e32 vcc, s99, v0
	s_cbranch_vccz .Lgs_np_2
	buffer_wbl2 sc1
.Lgs_np_2:
	global_load_dword v0, v1, s[26:27] sc1
	s_waitcnt vmcnt(0)
	v_cmp_le_u32_e32 vcc, s11, v0
	s_cbranch_vccnz .LBB0_407

; __device__ __forceinline__ int fresh_lane() { int l; asm volatile("v_mbcnt_lo_u32_b32 %0, -1, 0\n\tv_mbcnt_hi_u32_b32 %0, -1, %0" : "=v"(l)); return l; }
; __device__ __forceinline__ unsigned bar_ld(unsigned* p) { return __hip_atomic_load(p, __ATOMIC_RELAXED, __HIP_MEMORY_SCOPE_AGENT); }
; __device__ __forceinline__ unsigned bar_add(unsigned* p) { return __hip_atomic_fetch_add(p, 1u, __ATOMIC_RELAXED, __HIP_MEMORY_SCOPE_AGENT); }
; __device__ __forceinline__ void grid_bar(unsigned* bar, unsigned k, unsigned x, unsigned nloc, unsigned nx, int wave0) {
;     ...
;     if (wave0 == 0) {
;         const int ln = fresh_lane();
;         if (ln == 0) {
;             const unsigned old = bar_add(&bar[1024 + 64 * x]);
;             if (old + 1u == k * nloc) {
;                 __builtin_amdgcn_fence(__ATOMIC_RELEASE, "agent");
;                 asm volatile("s_waitcnt vmcnt(0)" ::: "memory");
;                 const unsigned og = bar_add(&bar[3072]);
;                 if (og + 1u == k * nx) bar_add(&bar[3136]);
;                 else while (bar_ld(&bar[3136]) < k) __builtin_amdgcn_s_sleep(1);
;                 __builtin_amdgcn_fence(__ATOMIC_ACQUIRE, "agent");
;                 bar_add(&bar[2048 + 64 * x]);
;                 asm volatile("s_waitcnt vmcnt(0)" ::: "memory");
;             } else {
;                 while (bar_ld(&bar[2048 + 64 * x]) < k) __builtin_amdgcn_s_sleep(1);
;                 __builtin_amdgcn_fence(__ATOMIC_ACQUIRE, "agent");
;                 asm volatile("s_waitcnt vmcnt(0)" ::: "memory");
;             }
.LBB0_489:
	s_or_b64 exec, exec, s[2:3]
	s_waitcnt vmcnt(0)
	v_readfirstlane_b32 s2, v2
	s_add_i32 s6, s56, 2
	s_nop 0
	v_add3_u32 v0, s2, v0, 1
	v_readlane_b32 s2, v255, 42
	s_mul_i32 s2, s6, s2
	s_nop 0
	s_mov_b32 s99, s2
	v_cmp_ne_u32_e32 vcc, s2, v0
	s_and_saveexec_b64 s[2:3], vcc
	s_xor_b64 s[2:3], exec, s[2:3]
	s_cbranch_execz .LBB0_493
	v_readlane_b32 s98, v255, 42
	s_sub_i32 s99, s99, s98
	s_add_i32 s99, s99, 1
	v_cmp_eq_u32_e32 vcc, s99, v0
	s_cbranch_vccz .Lgs_np_4
	buffer_wbl2 sc1

; __device__ __forceinline__ int fresh_lane() { int l; asm volatile("v_mbcnt_lo_u32_b32 %0, -1, 0\n\tv_mbcnt_hi_u32_b32 %0, -1, %0" : "=v"(l)); return l; }
; __device__ __forceinline__ unsigned bar_ld(unsigned* p) { return __hip_atomic_load(p, __ATOMIC_RELAXED, __HIP_MEMORY_SCOPE_AGENT); }
; __device__ __forceinline__ unsigned bar_add(unsigned* p) { return __hip_atomic_fetch_add(p, 1u, __ATOMIC_RELAXED, __HIP_MEMORY_SCOPE_AGENT); }
; __device__ __forceinline__ void grid_bar(unsigned* bar, unsigned k, unsigned x, unsigned nloc, unsigned nx, int wave0) {
;     ...
;     if (wave0 == 0) {
;         const int ln = fresh_lane();
;         if (ln == 0) {
;             const unsigned old = bar_add(&bar[1024 + 64 * x]);
;             if (old + 1u == k * nloc) {
;                 __builtin_amdgcn_fence(__ATOMIC_RELEASE, "agent");
;                 asm volatile("s_waitcnt vmcnt(0)" ::: "memory");
;                 const unsigned og = bar_add(&bar[3072]);
;                 if (og + 1u == k * nx) bar_add(&bar[3136]);
;                 else while (bar_ld(&bar[3136]) < k) __builtin_amdgcn_s_sleep(1);
;                 __builtin_amdgcn_fence(__ATOMIC_ACQUIRE, "agent");
;                 bar_add(&bar[2048 + 64 * x]);
;                 asm volatile("s_waitcnt vmcnt(0)" ::: "memory");
;             } else {
;                 while (bar_ld(&bar[2048 + 64 * x]) < k) __builtin_amdgcn_s_sleep(1);
;                 __builtin_amdgcn_fence(__ATOMIC_ACQUIRE, "agent");
;                 asm volatile("s_waitcnt vmcnt(0)" ::: "memory");
;             }
.LBB0_579:
	s_or_b64 exec, exec, s[4:5]
	s_waitcnt vmcnt(0)
	v_readfirstlane_b32 s1, v2
	s_add_i32 s0, s11, 1
	s_nop 0
	v_add3_u32 v0, s1, v0, 1
	v_readlane_b32 s1, v255, 42
	s_mul_i32 s1, s0, s1
	s_nop 0
	s_mov_b32 s99, s1
	v_cmp_ne_u32_e32 vcc, s1, v0
	s_and_saveexec_b64 s[4:5], vcc
	s_xor_b64 s[4:5], exec, s[4:5]
	s_cbranch_execz .LBB0_583
	v_readlane_b32 s98, v255, 42
	s_sub_i32 s99, s99, s98
	s_add_i32 s99, s99, 1
	v_cmp_eq_u32_e32 vcc, s99, v0
	s_cbranch_vccz .Lgs_np_6
	buffer_wbl2 sc1
.Lgs_np_6:
	global_load_dword v0, v1, s[26:27] sc1
	s_waitcnt vmcnt(0)
	v_cmp_le_u32_e32 vcc, s0, v0
	s_cbranch_vccnz .LBB0_582

; __device__ __forceinline__ int fresh_lane() { int l; asm volatile("v_mbcnt_lo_u32_b32 %0, -1, 0\n\tv_mbcnt_hi_u32_b32 %0, -1, %0" : "=v"(l)); return l; }
; __device__ __forceinline__ unsigned bar_ld(unsigned* p) { return __hip_atomic_load(p, __ATOMIC_RELAXED, __HIP_MEMORY_SCOPE_AGENT); }
; __device__ __forceinline__ unsigned bar_add(unsigned* p) { return __hip_atomic_fetch_add(p, 1u, __ATOMIC_RELAXED, __HIP_MEMORY_SCOPE_AGENT); }
; __device__ __forceinline__ void grid_bar(unsigned* bar, unsigned k, unsigned x, unsigned nloc, unsigned nx, int wave0) {
;     ...
;     if (wave0 == 0) {
;         const int ln = fresh_lane();
;         if (ln == 0) {
;             const unsigned old = bar_add(&bar[1024 + 64 * x]);
;             if (old + 1u == k * nloc) {
;                 __builtin_amdgcn_fence(__ATOMIC_RELEASE, "agent");
;                 asm volatile("s_waitcnt vmcnt(0)" ::: "memory");
;                 const unsigned og = bar_add(&bar[3072]);
;                 if (og + 1u == k * nx) bar_add(&bar[3136]);
;                 else while (bar_ld(&bar[3136]) < k) __builtin_amdgcn_s_sleep(1);
;                 __builtin_amdgcn_fence(__ATOMIC_ACQUIRE, "agent");
;                 bar_add(&bar[2048 + 64 * x]);
;                 asm volatile("s_waitcnt vmcnt(0)" ::: "memory");
;             } else {
;                 while (bar_ld(&bar[2048 + 64 * x]) < k) __builtin_amdgcn_s_sleep(1);
;                 __builtin_amdgcn_fence(__ATOMIC_ACQUIRE, "agent");
;                 asm volatile("s_waitcnt vmcnt(0)" ::: "memory");
;             }
.LBB0_668:
	s_or_b64 exec, exec, s[4:5]
	s_waitcnt vmcnt(0)
	v_readfirstlane_b32 s1, v2
	s_add_i32 s0, s11, 2
	s_nop 0
	v_add3_u32 v0, s1, v0, 1
	v_readlane_b32 s1, v255, 42
	s_mul_i32 s1, s0, s1
	s_nop 0
	s_mov_b32 s99, s1
	v_cmp_ne_u32_e32 vcc, s1, v0
	s_and_saveexec_b64 s[4:5], vcc
	s_xor_b64 s[4:5], exec, s[4:5]
	s_cbranch_execz .LBB0_672
	v_readlane_b32 s98, v255, 42
	s_sub_i32 s99, s99, s98
	s_add_i32 s99, s99, 1
	v_cmp_eq_u32_e32 vcc, s99, v0
	s_cbranch_vccz .Lgs_np_7
	buffer_wbl2 sc1

; __device__ __forceinline__ int fresh_lane() { int l; asm volatile("v_mbcnt_lo_u32_b32 %0, -1, 0\n\tv_mbcnt_hi_u32_b32 %0, -1, %0" : "=v"(l)); return l; }
; __device__ __forceinline__ unsigned bar_ld(unsigned* p) { return __hip_atomic_load(p, __ATOMIC_RELAXED, __HIP_MEMORY_SCOPE_AGENT); }
; __device__ __forceinline__ unsigned bar_add(unsigned* p) { return __hip_atomic_fetch_add(p, 1u, __ATOMIC_RELAXED, __HIP_MEMORY_SCOPE_AGENT); }
; __device__ __forceinline__ void grid_bar(unsigned* bar, unsigned k, unsigned x, unsigned nloc, unsigned nx, int wave0) {
;     ...
;     if (wave0 == 0) {
;         const int ln = fresh_lane();
;         if (ln == 0) {
;             const unsigned old = bar_add(&bar[1024 + 64 * x]);
;             if (old + 1u == k * nloc) {
;                 __builtin_amdgcn_fence(__ATOMIC_RELEASE, "agent");
;                 asm volatile("s_waitcnt vmcnt(0)" ::: "memory");
;                 const unsigned og = bar_add(&bar[3072]);
;                 if (og + 1u == k * nx) bar_add(&bar[3136]);
;                 else while (bar_ld(&bar[3136]) < k) __builtin_amdgcn_s_sleep(1);
;                 __builtin_amdgcn_fence(__ATOMIC_ACQUIRE, "agent");
;                 bar_add(&bar[2048 + 64 * x]);
;                 asm volatile("s_waitcnt vmcnt(0)" ::: "memory");
;             } else {
;                 while (bar_ld(&bar[2048 + 64 * x]) < k) __builtin_amdgcn_s_sleep(1);
;                 __builtin_amdgcn_fence(__ATOMIC_ACQUIRE, "agent");
;                 asm volatile("s_waitcnt vmcnt(0)" ::: "memory");
;             }
.LBB0_732:
	s_or_b64 exec, exec, s[6:7]
	s_waitcnt vmcnt(0)
	v_readfirstlane_b32 s0, v2
	s_nop 1
	v_add3_u32 v0, s0, v0, 1
	v_readlane_b32 s0, v255, 42
	s_mul_i32 s0, s56, s0
	s_nop 0
	s_mov_b32 s99, s0
	v_cmp_ne_u32_e32 vcc, s0, v0
	s_and_saveexec_b64 s[0:1], vcc
	s_xor_b64 s[6:7], exec, s[0:1]
	s_cbranch_execz .LBB0_736
	v_readlane_b32 s98, v255, 42
	s_sub_i32 s99, s99, s98
	s_add_i32 s99, s99, 1
	v_cmp_eq_u32_e32 vcc, s99, v0
	s_cbranch_vccz .Lgs_np_8
	buffer_wbl2 sc1
.Lgs_np_8:
	global_load_dword v0, v1, s[26:27] sc1
	s_waitcnt vmcnt(0)
	v_cmp_le_u32_e32 vcc, s56, v0
	s_cbranch_vccnz .LBB0_735

; __device__ __forceinline__ int fresh_lane() { int l; asm volatile("v_mbcnt_lo_u32_b32 %0, -1, 0\n\tv_mbcnt_hi_u32_b32 %0, -1, %0" : "=v"(l)); return l; }
; __device__ __forceinline__ unsigned bar_ld(unsigned* p) { return __hip_atomic_load(p, __ATOMIC_RELAXED, __HIP_MEMORY_SCOPE_AGENT); }
; __device__ __forceinline__ unsigned bar_add(unsigned* p) { return __hip_atomic_fetch_add(p, 1u, __ATOMIC_RELAXED, __HIP_MEMORY_SCOPE_AGENT); }
; __device__ __forceinline__ void grid_bar(unsigned* bar, unsigned k, unsigned x, unsigned nloc, unsigned nx, int wave0) {
;     ...
;     if (wave0 == 0) {
;         const int ln = fresh_lane();
;         if (ln == 0) {
;             const unsigned old = bar_add(&bar[1024 + 64 * x]);
;             if (old + 1u == k * nloc) {
;                 __builtin_amdgcn_fence(__ATOMIC_RELEASE, "agent");
;                 asm volatile("s_waitcnt vmcnt(0)" ::: "memory");
;                 const unsigned og = bar_add(&bar[3072]);
;                 if (og + 1u == k * nx) bar_add(&bar[3136]);
;                 else while (bar_ld(&bar[3136]) < k) __builtin_amdgcn_s_sleep(1);
;                 __builtin_amdgcn_fence(__ATOMIC_ACQUIRE, "agent");
;                 bar_add(&bar[2048 + 64 * x]);
;                 asm volatile("s_waitcnt vmcnt(0)" ::: "memory");
;             } else {
;                 while (bar_ld(&bar[2048 + 64 * x]) < k) __builtin_amdgcn_s_sleep(1);
;                 __builtin_amdgcn_fence(__ATOMIC_ACQUIRE, "agent");
;                 asm volatile("s_waitcnt vmcnt(0)" ::: "memory");
;             }
.LBB0_845:
	s_or_b64 exec, exec, s[2:3]
	s_waitcnt vmcnt(0)
	v_readfirstlane_b32 s2, v2
	s_nop 1
	v_add3_u32 v0, s2, v0, 1
	v_readlane_b32 s2, v255, 42
	s_mul_i32 s2, s56, s2
	s_nop 0
	s_mov_b32 s99, s2
	v_cmp_ne_u32_e32 vcc, s2, v0
	s_and_saveexec_b64 s[2:3], vcc
	s_xor_b64 s[2:3], exec, s[2:3]
	s_cbranch_execz .LBB0_849
	v_readlane_b32 s98, v255, 42
	s_sub_i32 s99, s99, s98
	s_add_i32 s99, s99, 1
	v_cmp_eq_u32_e32 vcc, s99, v0
	s_cbranch_vccz .Lgs_np_9
	buffer_wbl2 sc1
